# v16: + LDS-DMA issue of tile i+2 moved below the K/V fragment reads (attention), on top of v15
# baseline (speedup 1.0000x reference)
;     ...
;     for (int i = 0; i < ntiles; ++i) {
;         const int b2 = (b == 0) ? 2 : b - 1;
;         if (i + 2 < ntiles) ATT_LOAD(i + 2, b2);
;         bool need = true, selme = true; int kt = 0; bool own = false;
;         if (MOBA) {
;             if (i < 4 * j) { selme = (selmask >> (i >> 2)) & 1u; need = __builtin_amdgcn_ballot_w64(selme) != 0ull; }
;             else { own = true; kt = i - 4 * j; need = kt <= (w >> 1); }
.LBB0_404:
	s_add_i32 s2, s77, 2
	s_cmp_ge_u32 s2, s11
	s_cselect_b64 s[66:67], -1, 0
	s_and_b64 vcc, exec, s[66:67]
.LBB0_406:
	s_cmp_ge_u32 s77, s5
	s_cselect_b64 s[68:69], -1, 0
	s_mov_b64 s[72:73], -1
	s_and_b64 vcc, exec, s[68:69]
	s_cbranch_vccz .LBB0_411
	s_andn2_b64 vcc, exec, s[72:73]
	s_mov_b32 s72, 0
	s_cbranch_vccz .LBB0_412

;     ...
;         if (i + 2 < ntiles) ATT_LOAD(i + 2, b2);
.LBB0_409:
	s_and_b64 vcc, exec, s[66:67]
	s_cbranch_vccnz .Latt_dma_skipB
	s_lshl_b32 s98, s75, 14
	s_addk_i32 s98, 0xc000
	s_cmp_lg_u32 s75, 0
	s_cselect_b32 s98, s98, 0x8000
	s_add_i32 s98, s95, s98
	v_lshl_add_u64 v[216:217], s[14:15], 0, v[150:151]
	s_mov_b32 m0, s98
	s_nop 0
	global_load_lds_dwordx4 v[216:217], off
	v_lshl_add_u64 v[216:217], s[14:15], 0, v[156:157]
	s_add_i32 m0, s98, 0xc000
	s_nop 0
	global_load_lds_dwordx4 v[216:217], off
	v_lshl_add_u64 v[216:217], s[14:15], 0, v[152:153]
	s_add_i32 m0, s98, 0x400
	s_nop 0
	global_load_lds_dwordx4 v[216:217], off
	v_lshl_add_u64 v[216:217], s[14:15], 0, v[158:159]
	s_add_i32 m0, s98, 0xc400
	s_nop 0
	global_load_lds_dwordx4 v[216:217], off

; #define LAS __attribute__((address_space(3)))
;     ...
;             const LAS unsigned char* kb_ = lds + ATT_KB + b * 16384;
;             const LAS unsigned char* vb_ = lds + ATT_VB + b * 16384;
;             f32x16 st[2];
;             bf16x8 ka[8];
; #pragma unroll
;             for (int ks = 0; ks < 8; ++ks) ka[ks] = *(const LAS bf16x8*)(kb_ + (kbase ^ (unsigned)(ks << 5)));
;             bf16x8 va[2][4];
; #pragma unroll
;             for (int dt = 0; dt < 4; ++dt) va[0][dt] = *(const LAS bf16x8*)(vb_ + dt * 4096 + vbase);
; #pragma unroll
;             for (int rt = 0; rt < 2; ++rt)
; #pragma unroll
;                 for (int r = 0; r < 16; ++r) st[rt][r] = 0.f;
;             __builtin_amdgcn_sched_barrier(0);
;             __builtin_amdgcn_s_setprio(1);
; #pragma unroll
;             for (int ks = 0; ks < 8; ++ks) { st[0] = __builtin_amdgcn_mfma_f32_32x32x16_bf16(ka[ks], qf[ks], st[0], 0, 0, 0);
;                 ka[ks] = *(const LAS bf16x8*)(kb_ + 8192 + (kbase ^ (unsigned)(ks << 5))); __builtin_amdgcn_sched_barrier(0); }
; #pragma unroll
;             for (int ks = 0; ks < 8; ++ks) st[1] = __builtin_amdgcn_mfma_f32_32x32x16_bf16(ka[ks], qf[ks], st[1], 0, 0, 0);
;             __builtin_amdgcn_s_setprio(0);
;             if (MOBA) {
;                 if (own && 64 * kt + 63 > 32 * w) {
;                     const int qloc = 32 * w + ql;
; #pragma unroll
;                     for (int rt = 0; rt < 2; ++rt)
; #pragma unroll
;                         for (int r = 0; r < 16; ++r) { const int key = 64 * kt + 32 * rt + 16 * (r >> 3) + 8 * h2 + (r & 7); if (key > qloc) st[rt][r] = NEGBIG; }
;                 }
.LBB0_413:
	s_lshl_b32 s34, s75, 14
	s_add_i32 s70, s34, 0
	v_add_u32_e32 v2, s70, v161
	v_add_u32_e32 v17, s70, v164
	v_add_u32_e32 v204, s70, v166
	v_add_u32_e32 v212, s70, v168
	v_add_u32_e32 v4, s70, v162
	v_add_u32_e32 v16, s70, v163
	ds_read_b128 v[82:85], v2
	ds_read_b128 v[98:101], v16
	v_add_u32_e32 v175, s70, v165
	ds_read_b128 v[102:105], v17
	ds_read_b128 v[106:109], v175
	v_add_u32_e32 v208, s70, v167
	ds_read_b128 v[110:113], v204
	ds_read_b128 v[176:179], v208
	v_add_u32_e32 v213, s70, v169
	ds_read_b128 v[180:183], v212
	ds_read_b128 v[184:187], v213
	ds_read_b128 v[146:149], v4 offset:49152
	ds_read_b128 v[12:15], v4 offset:53248
	ds_read_b128 v[8:11], v4 offset:57344
	ds_read_b128 v[4:7], v4 offset:61440
	s_and_b64 vcc, exec, s[66:67]
	s_cbranch_vccnz .Latt_dma_skipA
	s_lshl_b32 s98, s75, 14
	s_addk_i32 s98, 0xc000
	s_cmp_lg_u32 s75, 0
	s_cselect_b32 s98, s98, 0x8000
	s_add_i32 s98, s95, s98
	v_lshl_add_u64 v[216:217], s[14:15], 0, v[150:151]
	s_mov_b32 m0, s98
	s_nop 0
	global_load_lds_dwordx4 v[216:217], off
	v_lshl_add_u64 v[216:217], s[14:15], 0, v[156:157]
	s_add_i32 m0, s98, 0xc000
	s_nop 0
	global_load_lds_dwordx4 v[216:217], off
	v_lshl_add_u64 v[216:217], s[14:15], 0, v[152:153]
	s_add_i32 m0, s98, 0x400
	s_nop 0
	global_load_lds_dwordx4 v[216:217], off
	v_lshl_add_u64 v[216:217], s[14:15], 0, v[158:159]
	s_add_i32 m0, s98, 0xc400
	s_nop 0
	global_load_lds_dwordx4 v[216:217], off
.Latt_dma_skipA:
	s_setprio 1
	s_waitcnt lgkmcnt(11)
	v_mfma_f32_32x32x16_bf16 v[82:97], v[82:85], v[114:117], 0
	ds_read_b128 v[188:191], v2 offset:8192
	s_waitcnt lgkmcnt(11)
	v_mfma_f32_32x32x16_bf16 v[82:97], v[98:101], v[118:121], v[82:97]
	ds_read_b128 v[192:195], v16 offset:8192
	s_waitcnt lgkmcnt(11)
	v_mfma_f32_32x32x16_bf16 v[82:97], v[102:105], v[122:125], v[82:97]
	ds_read_b128 v[196:199], v17 offset:8192
	s_waitcnt lgkmcnt(11)
	v_mfma_f32_32x32x16_bf16 v[82:97], v[106:109], v[126:129], v[82:97]
	ds_read_b128 v[200:203], v175 offset:8192
	s_waitcnt lgkmcnt(11)
	v_mfma_f32_32x32x16_bf16 v[82:97], v[110:113], v[130:133], v[82:97]
	ds_read_b128 v[204:207], v204 offset:8192
	s_waitcnt lgkmcnt(11)
	v_mfma_f32_32x32x16_bf16 v[82:97], v[176:179], v[134:137], v[82:97]
	ds_read_b128 v[208:211], v208 offset:8192
	s_waitcnt lgkmcnt(11)
	v_mfma_f32_32x32x16_bf16 v[82:97], v[180:183], v[138:141], v[82:97]
	ds_read_b128 v[176:179], v212 offset:8192
	s_waitcnt lgkmcnt(11)
	v_mfma_f32_32x32x16_bf16 v[82:97], v[184:187], v[142:145], v[82:97]
	ds_read_b128 v[180:183], v213 offset:8192
	s_waitcnt lgkmcnt(7)
	v_mfma_f32_32x32x16_bf16 v[98:113], v[188:191], v[114:117], 0
	s_waitcnt lgkmcnt(6)
	v_mfma_f32_32x32x16_bf16 v[98:113], v[192:195], v[118:121], v[98:113]
	s_waitcnt lgkmcnt(5)
	v_mfma_f32_32x32x16_bf16 v[98:113], v[196:199], v[122:125], v[98:113]
	s_waitcnt lgkmcnt(4)
	v_mfma_f32_32x32x16_bf16 v[98:113], v[200:203], v[126:129], v[98:113]
	s_waitcnt lgkmcnt(3)
	v_mfma_f32_32x32x16_bf16 v[98:113], v[204:207], v[130:133], v[98:113]
	s_waitcnt lgkmcnt(2)
	v_mfma_f32_32x32x16_bf16 v[98:113], v[208:211], v[134:137], v[98:113]
	s_waitcnt lgkmcnt(1)
	v_mfma_f32_32x32x16_bf16 v[98:113], v[176:179], v[138:141], v[98:113]
	s_waitcnt lgkmcnt(0)
	v_mfma_f32_32x32x16_bf16 v[98:113], v[180:183], v[142:145], v[98:113]
	s_setprio 0
	s_or_b32 s34, s72, 63
	s_cmp_gt_i32 s34, s96
	s_cselect_b64 s[34:35], -1, 0
	s_and_b64 s[34:35], s[68:69], s[34:35]
	s_andn2_b64 vcc, exec, s[34:35]
	s_cbranch_vccnz .LBB0_415
	v_or_b32_e32 v2, s72, v155
	v_cmp_gt_i32_e32 vcc, v2, v154
	s_nop 1
	v_cndmask_b32_e32 v16, v82, v232, vcc
	v_cmp_lt_i32_e32 vcc, v2, v154
	s_nop 1
	v_cndmask_b32_e32 v82, v16, v82, vcc
	v_or_b32_e32 v16, 2, v2
	v_cndmask_b32_e32 v83, v232, v83, vcc
	v_cmp_le_i32_e32 vcc, v16, v154
	v_or_b32_e32 v16, 3, v2
	s_nop 0
	v_cndmask_b32_e32 v84, v232, v84, vcc
	v_cmp_le_i32_e32 vcc, v16, v154
	v_or_b32_e32 v16, 4, v2
	s_nop 0
	v_cndmask_b32_e32 v85, v232, v85, vcc
	v_cmp_le_i32_e32 vcc, v16, v154
	v_or_b32_e32 v16, 5, v2
	s_nop 0
	v_cndmask_b32_e32 v86, v232, v86, vcc
	v_cmp_le_i32_e32 vcc, v16, v154
	v_or_b32_e32 v16, 6, v2
	s_nop 0
	v_cndmask_b32_e32 v87, v232, v87, vcc
	v_cmp_le_i32_e32 vcc, v16, v154
	v_or_b32_e32 v16, 7, v2
	s_nop 0
	v_cndmask_b32_e32 v88, v232, v88, vcc
	v_cmp_le_i32_e32 vcc, v16, v154
	v_or_b32_e32 v16, 16, v2
	s_nop 0
	v_cndmask_b32_e32 v89, v232, v89, vcc
	v_cmp_le_i32_e32 vcc, v16, v154
	v_or_b32_e32 v16, 17, v2
	s_nop 0
	v_cndmask_b32_e32 v90, v232, v90, vcc
	v_cmp_le_i32_e32 vcc, v16, v154
	v_or_b32_e32 v16, 18, v2
	s_nop 0
	v_cndmask_b32_e32 v91, v232, v91, vcc
	v_cmp_le_i32_e32 vcc, v16, v154
	v_or_b32_e32 v16, 19, v2
	s_nop 0
	v_cndmask_b32_e32 v92, v232, v92, vcc
	v_cmp_le_i32_e32 vcc, v16, v154
	v_or_b32_e32 v16, 20, v2
	s_nop 0
	v_cndmask_b32_e32 v93, v232, v93, vcc
	v_cmp_le_i32_e32 vcc, v16, v154
	v_or_b32_e32 v16, 21, v2
	s_nop 0
	v_cndmask_b32_e32 v94, v232, v94, vcc
	v_cmp_le_i32_e32 vcc, v16, v154
	v_or_b32_e32 v16, 22, v2
	s_nop 0
	v_cndmask_b32_e32 v95, v232, v95, vcc
	v_cmp_le_i32_e32 vcc, v16, v154
	v_or_b32_e32 v16, 23, v2
	s_nop 0
	v_cndmask_b32_e32 v96, v232, v96, vcc
	v_cmp_le_i32_e32 vcc, v16, v154
	v_or_b32_e32 v16, 32, v2
	s_nop 0
	v_cndmask_b32_e32 v97, v232, v97, vcc
	v_cmp_le_i32_e32 vcc, v16, v154
	v_or_b32_e32 v16, 33, v2
	s_nop 0
	v_cndmask_b32_e32 v98, v232, v98, vcc
	v_cmp_le_i32_e32 vcc, v16, v154
	v_or_b32_e32 v16, 34, v2
	s_nop 0
	v_cndmask_b32_e32 v99, v232, v99, vcc
	v_cmp_le_i32_e32 vcc, v16, v154
	v_or_b32_e32 v16, 35, v2
	s_nop 0
	v_cndmask_b32_e32 v100, v232, v100, vcc
	v_cmp_le_i32_e32 vcc, v16, v154
	v_or_b32_e32 v16, 36, v2
	s_nop 0
	v_cndmask_b32_e32 v101, v232, v101, vcc
	v_cmp_le_i32_e32 vcc, v16, v154
	v_or_b32_e32 v16, 37, v2
	s_nop 0
	v_cndmask_b32_e32 v102, v232, v102, vcc
	v_cmp_le_i32_e32 vcc, v16, v154
	v_or_b32_e32 v16, 38, v2
	s_nop 0
	v_cndmask_b32_e32 v103, v232, v103, vcc
	v_cmp_le_i32_e32 vcc, v16, v154
	v_or_b32_e32 v16, 39, v2
	s_nop 0
	v_cndmask_b32_e32 v104, v232, v104, vcc
	v_cmp_le_i32_e32 vcc, v16, v154
	v_or_b32_e32 v16, 48, v2
	s_nop 0
	v_cndmask_b32_e32 v105, v232, v105, vcc
	v_cmp_le_i32_e32 vcc, v16, v154
	v_or_b32_e32 v16, 49, v2
	s_nop 0
	v_cndmask_b32_e32 v106, v232, v106, vcc
	v_cmp_le_i32_e32 vcc, v16, v154
	v_or_b32_e32 v16, 50, v2
	s_nop 0
	v_cndmask_b32_e32 v107, v232, v107, vcc
	v_cmp_le_i32_e32 vcc, v16, v154
	v_or_b32_e32 v16, 51, v2
	s_nop 0
	v_cndmask_b32_e32 v108, v232, v108, vcc
	v_cmp_le_i32_e32 vcc, v16, v154
	v_or_b32_e32 v16, 52, v2
	s_nop 0
	v_cndmask_b32_e32 v109, v232, v109, vcc
	v_cmp_le_i32_e32 vcc, v16, v154
	v_or_b32_e32 v16, 53, v2
	s_nop 0
	v_cndmask_b32_e32 v110, v232, v110, vcc
	v_cmp_le_i32_e32 vcc, v16, v154
	v_or_b32_e32 v16, 54, v2
	v_or_b32_e32 v2, 55, v2
	v_cndmask_b32_e32 v111, v232, v111, vcc
	v_cmp_le_i32_e32 vcc, v16, v154
	s_nop 1
	v_cndmask_b32_e32 v112, v232, v112, vcc
	v_cmp_le_i32_e32 vcc, v2, v154
	s_nop 1
	v_cndmask_b32_e32 v113, v232, v113, vcc

; __global__ void __launch_bounds__(512, 2) fwd(Args a) {
	.amdhsa_kernel _Z3fwd4Args
		.amdhsa_group_segment_fixed_size 0
		.amdhsa_private_segment_fixed_size 0
		.amdhsa_kernarg_size 480
		.amdhsa_user_sgpr_count 2
		.amdhsa_user_sgpr_dispatch_ptr 0
		.amdhsa_user_sgpr_queue_ptr 0
		.amdhsa_user_sgpr_kernarg_segment_ptr 1
		.amdhsa_user_sgpr_dispatch_id 0
		.amdhsa_user_sgpr_kernarg_preload_length 0
		.amdhsa_user_sgpr_kernarg_preload_offset 0
		.amdhsa_user_sgpr_private_segment_size 0
		.amdhsa_uses_dynamic_stack 0
		.amdhsa_enable_private_segment 0
		.amdhsa_system_sgpr_workgroup_id_x 1
		.amdhsa_system_sgpr_workgroup_id_y 0
		.amdhsa_system_sgpr_workgroup_id_z 0
		.amdhsa_system_sgpr_workgroup_info 0
		.amdhsa_system_vgpr_workitem_id 0
		.amdhsa_next_free_vgpr 256
		.amdhsa_next_free_sgpr 102
		.amdhsa_accum_offset 256
		.amdhsa_reserve_vcc 1
		.amdhsa_float_round_mode_32 0
		.amdhsa_float_round_mode_16_64 0
		.amdhsa_float_denorm_mode_32 3
		.amdhsa_float_denorm_mode_16_64 3
		.amdhsa_dx10_clamp 1
		.amdhsa_ieee_mode 1
		.amdhsa_fp16_overflow 0
		.amdhsa_tg_split 0
		.amdhsa_exception_fp_ieee_invalid_op 0
		.amdhsa_exception_fp_denorm_src 0
		.amdhsa_exception_fp_ieee_div_zero 0
		.amdhsa_exception_fp_ieee_overflow 0
		.amdhsa_exception_fp_ieee_underflow 0
		.amdhsa_exception_fp_ieee_inexact 0
		.amdhsa_exception_int_div_zero 0
	.end_amdhsa_kernel

; __global__ void __launch_bounds__(512, 2) fwd(Args a) {
amdhsa.kernels:
  - .agpr_count:     0
    .args:
      - .offset:         0
        .size:           224
        .value_kind:     by_value
      - .offset:         224
        .size:           4
        .value_kind:     hidden_block_count_x
      - .offset:         228
        .size:           4
        .value_kind:     hidden_block_count_y
      - .offset:         232
        .size:           4
        .value_kind:     hidden_block_count_z
      - .offset:         236
        .size:           2
        .value_kind:     hidden_group_size_x
      - .offset:         238
        .size:           2
        .value_kind:     hidden_group_size_y
      - .offset:         240
        .size:           2
        .value_kind:     hidden_group_size_z
      - .offset:         242
        .size:           2
        .value_kind:     hidden_remainder_x
      - .offset:         244
        .size:           2
        .value_kind:     hidden_remainder_y
      - .offset:         246
        .size:           2
        .value_kind:     hidden_remainder_z
      - .offset:         264
        .size:           8
        .value_kind:     hidden_global_offset_x
      - .offset:         272
        .size:           8
        .value_kind:     hidden_global_offset_y
      - .offset:         280
        .size:           8
        .value_kind:     hidden_global_offset_z
      - .offset:         288
        .size:           2
        .value_kind:     hidden_grid_dims
      - .offset:         312
        .size:           8
        .value_kind:     hidden_multigrid_sync_arg
      - .offset:         344
        .size:           4
        .value_kind:     hidden_dynamic_lds_size
    .group_segment_fixed_size: 0
    .kernarg_segment_align: 8
    .kernarg_segment_size: 480
    .language:       OpenCL C
    .language_version:
      - 2
      - 0
    .max_flat_workgroup_size: 512
    .name:           _Z3fwd4Args
    .private_segment_fixed_size: 0
    .sgpr_count:     108
    .sgpr_spill_count: 15
    .symbol:         _Z3fwd4Args.kd
    .uniform_work_group_size: 1
    .uses_dynamic_stack: false
    .vgpr_count:     256
    .vgpr_spill_count: 0
    .wavefront_size: 64
